# non-final residual epilogue rewritten: 16 B residual loads and stores, loads kept in flight across rows, rss sums reduced with lane swaps and one atomic per four rows
# speedup vs baseline: 1.0448x; 1.0196x over previous
; template <int K>
; __device__ __forceinline__ void epilogue(const f32x4 (&acc)[2][2][4][2], const Unit& u, const EpiDesc& E, const Ctx& C, int wr, int wc, int fr, int fq) {
;     ...
;     } else if (K == EK_RESID) {
; #pragma unroll
;         for (int ai = 0; ai < 2; ++ai)
; #pragma unroll
;         for (int mh = 0; mh < 2; ++mh) {
;             u32x2 h[2][2][2];
; #pragma unroll
;             for (int m2 = 0; m2 < 2; ++m2)
; #pragma unroll
;                 for (int bj = 0; bj < 2; ++bj)
; #pragma unroll
;                     for (int n = 0; n < 2; ++n) h[m2][bj][n] = *(const u32x2*)(C.XB + (size_t)(row0 + 128 * ai + 16 * (2 * mh + m2)) * DM + 256 * u.pn + 128 * bj + 16 * n + lc0);
; #pragma unroll
;             for (int m2 = 0; m2 < 2; ++m2) {
;                 const int m = 2 * mh + m2;
;                 const int row = row0 + 128 * ai + 16 * m;
;                 float* dst = C.PA + (size_t)row * DM;
;                 if (E.final_) {
;                     if (row < NPR) { const int b = row / TP, t = row - b * TP; if (t >= 16) dst = C.out + OFF_YP + ((size_t)b * 4096 + (t - 16)) * 1024; }
;                     else if (row < MR) dst = C.out + OFF_YS + (size_t)(row - NPR) * 1024;
;                 }
.LBB0_250:
	s_cmp_eq_u32 s24, 1
	s_cbranch_scc0 .LBB0_454
	s_and_b64 vcc, exec, s[52:53]
	s_cbranch_vccz .Lres_new
	s_lshl_b32 s22, s87, 8
	s_add_i32 s22, s22, s74
	v_or_b32_e32 v144, s22, v172
	s_lshl_b32 s2, s86, 8
	s_ashr_i32 s3, s2, 31
	v_ashrrev_i32_e32 v145, 31, v144
	v_lshl_add_u64 v[148:149], s[2:3], 1, v[138:139]
	s_waitcnt lgkmcnt(0)
	v_lshlrev_b64 v[130:131], 11, v[144:145]
	v_or_b32_e32 v156, 16, v144
	v_lshl_add_u64 v[132:133], v[148:149], 0, v[130:131]
	v_ashrrev_i32_e32 v157, 31, v156
	global_load_dwordx2 v[130:131], v[132:133], off
	global_load_dwordx2 v[170:171], v[132:133], off offset:32
	global_load_dwordx2 v[164:165], v[132:133], off offset:256
	global_load_dwordx2 v[162:163], v[132:133], off offset:288
	v_lshlrev_b64 v[132:133], 11, v[156:157]
	v_lshl_add_u64 v[132:133], v[148:149], 0, v[132:133]
	global_load_dwordx2 v[158:159], v[132:133], off
	global_load_dwordx2 v[154:155], v[132:133], off offset:32
	global_load_dwordx2 v[152:153], v[132:133], off offset:256
	global_load_dwordx2 v[150:151], v[132:133], off offset:288
	v_lshlrev_b64 v[132:133], 12, v[144:145]
	v_cndmask_b32_e64 v0, 0, 1, s[52:53]
	v_cmp_ne_u32_e64 s[42:43], 1, v0
	s_andn2_b64 vcc, exec, s[52:53]
	v_lshl_add_u64 v[160:161], s[94:95], 0, v[132:133]
	s_cbranch_vccnz .LBB0_257
	s_movk_i32 s3, 0x403f
	v_cmp_lt_i32_e32 vcc, s3, v144
	s_and_saveexec_b64 s[20:21], vcc
	s_xor_b64 s[20:21], exec, s[20:21]
	s_cbranch_execz .LBB0_254
	v_add_u32_e32 v0, 0xffffbfc0, v144
	v_readlane_b32 s28, v252, 14
	s_cmpk_lt_u32 s22, 0x4240
	v_lshlrev_b64 v[132:133], 12, v[0:1]
	v_readlane_b32 s29, v252, 15
	s_cselect_b64 vcc, -1, 0
	s_nop 0
	v_lshl_add_u64 v[132:133], s[28:29], 0, v[132:133]
	v_cndmask_b32_e32 v161, v161, v133, vcc
	v_cndmask_b32_e32 v160, v160, v132, vcc

; __device__ __forceinline__ u32x2 pk4(f32x4 v) { u32x2 r; r.x = cvt_pk_bf16(v[0], v[1]); r.y = cvt_pk_bf16(v[2], v[3]); return r; }
; template <int K>
; __device__ __forceinline__ void epilogue(const f32x4 (&acc)[2][2][4][2], const Unit& u, const EpiDesc& E, const Ctx& C, int wr, int wc, int fr, int fq) {
;     ...
; #pragma unroll
;         for (int ai = 0; ai < 2; ++ai)
; #pragma unroll
;         for (int mh = 0; mh < 2; ++mh) {
;             u32x2 h[2][2][2];
; #pragma unroll
;             for (int m2 = 0; m2 < 2; ++m2)
; #pragma unroll
;                 for (int bj = 0; bj < 2; ++bj)
; #pragma unroll
;                     for (int n = 0; n < 2; ++n) h[m2][bj][n] = *(const u32x2*)(C.XB + (size_t)(row0 + 128 * ai + 16 * (2 * mh + m2)) * DM + 256 * u.pn + 128 * bj + 16 * n + lc0);
; #pragma unroll
;             for (int m2 = 0; m2 < 2; ++m2) {
;                 const int m = 2 * mh + m2;
;                 const int row = row0 + 128 * ai + 16 * m;
;                 float* dst = C.PA + (size_t)row * DM;
;                 if (E.final_) {
;                     if (row < NPR) { const int b = row / TP, t = row - b * TP; if (t >= 16) dst = C.out + OFF_YP + ((size_t)b * 4096 + (t - 16)) * 1024; }
;                     else if (row < MR) dst = C.out + OFF_YS + (size_t)(row - NPR) * 1024;
;                 }
;                 float ss = 0.f;
; #pragma unroll
;                 for (int bj = 0; bj < 2; ++bj)
; #pragma unroll
;                     for (int n = 0; n < 2; ++n) {
;                         const int col = 256 * u.pn + 128 * bj + 16 * n + lc0;
;                         const f32x4 hv = unpk4(h[m2][bj][n]) + acc[ai][bj][m][n] * E.alpha;
;                         if (E.final_) *(f32x4*)(dst + col) = hv;
;                         else {
;                             *(u32x2*)(C.XB + (size_t)row * DM + col) = pk4(hv);
;                             ss += hv[0] * hv[0] + hv[1] * hv[1] + hv[2] * hv[2] + hv[3] * hv[3];
;                         }
;                     }
;                 if (!E.final_) {
;                     ss += __shfl_xor(ss, 16); ss += __shfl_xor(ss, 32);
;                     if (fq == 0) unsafeAtomicAdd(E.rss_out + row, ss);
;                 }
.Lres_new:
	s_lshl_b32 s22, s87, 8
	s_add_i32 s22, s22, s74
	v_or_b32_e32 v132, s22, v172
	v_readlane_b32 s2, v254, 29
	v_readlane_b32 s3, v254, 30
	v_lshl_or_b32 v165, s86, 8, v175
	v_lshlrev_b32_e32 v0, 11, v132
	v_lshl_add_u32 v0, v165, 1, v0
	v_and_b32_e32 v165, 16, v233
	v_lshrrev_b32_e32 v133, 1, v165
	v_add_u32_e32 v165, v165, v133
	v_add_u32_e32 v0, v0, v165
	v_mov_b32_e32 v164, v0
	v_and_b32_e32 v165, 0x30, v233
	v_add_u32_e32 v132, v132, v165
	v_lshlrev_b32_e32 v132, 2, v132
	s_waitcnt lgkmcnt(0)
	global_load_dwordx4 v[144:147], v0, s[2:3]
	global_load_dwordx4 v[148:151], v0, s[2:3] offset:256
	v_add_u32_e32 v0, 0x8000, v0
	global_load_dwordx4 v[152:155], v0, s[2:3]
	global_load_dwordx4 v[156:159], v0, s[2:3] offset:256
	v_add_u32_e32 v0, 0x8000, v0
	s_waitcnt vmcnt(2)
	v_permlane16_swap_b32_e32 v144, v146
	v_permlane16_swap_b32_e32 v145, v147
	v_permlane16_swap_b32_e32 v148, v150
	v_permlane16_swap_b32_e32 v149, v151
	v_lshlrev_b32_e32 v178, 16, v144
	v_lshlrev_b32_e32 v179, 16, v145
	v_lshlrev_b32_e32 v180, 16, v146
	v_lshlrev_b32_e32 v181, 16, v147
	v_and_b32_e32 v144, 0xffff0000, v144
	v_and_b32_e32 v145, 0xffff0000, v145
	v_and_b32_e32 v146, 0xffff0000, v146
	v_and_b32_e32 v147, 0xffff0000, v147
	v_fma_f32 v122, v122, s10, v178
	v_fma_f32 v123, v123, s10, v144
	v_fma_f32 v124, v124, s10, v179
	v_fma_f32 v125, v125, s10, v145
	v_fma_f32 v126, v126, s10, v180
	v_fma_f32 v127, v127, s10, v146
	v_fma_f32 v128, v128, s10, v181
	v_fma_f32 v129, v129, s10, v147
	v_mul_f32_e32 v130, v122, v122
	v_mul_f32_e32 v131, v123, v123
	v_fmac_f32_e32 v130, v124, v124
	v_fmac_f32_e32 v131, v125, v125
	v_fmac_f32_e32 v130, v126, v126
	v_fmac_f32_e32 v131, v127, v127
	v_fmac_f32_e32 v130, v128, v128
	v_fmac_f32_e32 v131, v129, v129
	v_cvt_pk_bf16_f32 v144, v122, v123
	v_cvt_pk_bf16_f32 v145, v124, v125
	v_cvt_pk_bf16_f32 v146, v126, v127
	v_cvt_pk_bf16_f32 v147, v128, v129
	v_lshlrev_b32_e32 v178, 16, v148
	v_lshlrev_b32_e32 v179, 16, v149
	v_lshlrev_b32_e32 v180, 16, v150
	v_lshlrev_b32_e32 v181, 16, v151
	v_and_b32_e32 v148, 0xffff0000, v148
	v_and_b32_e32 v149, 0xffff0000, v149
	v_and_b32_e32 v150, 0xffff0000, v150
	v_and_b32_e32 v151, 0xffff0000, v151
	v_fma_f32 v114, v114, s10, v178
	v_fma_f32 v115, v115, s10, v148
	v_fma_f32 v116, v116, s10, v179
	v_fma_f32 v117, v117, s10, v149
	v_fma_f32 v118, v118, s10, v180
	v_fma_f32 v119, v119, s10, v150
	v_fma_f32 v120, v120, s10, v181
	v_fma_f32 v121, v121, s10, v151
	v_fmac_f32_e32 v130, v114, v114
	v_fmac_f32_e32 v131, v115, v115
	v_fmac_f32_e32 v130, v116, v116
	v_fmac_f32_e32 v131, v117, v117
	v_fmac_f32_e32 v130, v118, v118
	v_fmac_f32_e32 v131, v119, v119
	v_fmac_f32_e32 v130, v120, v120
	v_fmac_f32_e32 v131, v121, v121
	v_cvt_pk_bf16_f32 v148, v114, v115
	v_cvt_pk_bf16_f32 v149, v116, v117
	v_cvt_pk_bf16_f32 v150, v118, v119
	v_cvt_pk_bf16_f32 v151, v120, v121
	v_add_f32_e32 v168, v130, v131
	s_nop 0
	v_permlane16_swap_b32_e32 v144, v146
	v_permlane16_swap_b32_e32 v145, v147
	v_permlane16_swap_b32_e32 v148, v150
	v_permlane16_swap_b32_e32 v149, v151
	global_store_dwordx4 v164, v[144:147], s[2:3]
	global_store_dwordx4 v164, v[148:151], s[2:3] offset:256
	v_add_u32_e32 v164, 0x8000, v164
	global_load_dwordx4 v[160:163], v0, s[2:3]
	global_load_dwordx4 v[122:125], v0, s[2:3] offset:256
	v_add_u32_e32 v0, 0x8000, v0
	global_load_dwordx4 v[126:129], v0, s[2:3]
	global_load_dwordx4 v[114:117], v0, s[2:3] offset:256
	v_add_u32_e32 v0, 0x28000, v0
	s_waitcnt vmcnt(6)
	v_permlane16_swap_b32_e32 v152, v154
	v_permlane16_swap_b32_e32 v153, v155
	v_permlane16_swap_b32_e32 v156, v158
	v_permlane16_swap_b32_e32 v157, v159
	v_lshlrev_b32_e32 v178, 16, v152
	v_lshlrev_b32_e32 v179, 16, v153
	v_lshlrev_b32_e32 v180, 16, v154
	v_lshlrev_b32_e32 v181, 16, v155
	v_and_b32_e32 v152, 0xffff0000, v152
	v_and_b32_e32 v153, 0xffff0000, v153
	v_and_b32_e32 v154, 0xffff0000, v154
	v_and_b32_e32 v155, 0xffff0000, v155
	v_fma_f32 v106, v106, s10, v178
	v_fma_f32 v107, v107, s10, v152
	v_fma_f32 v108, v108, s10, v179
	v_fma_f32 v109, v109, s10, v153
	v_fma_f32 v110, v110, s10, v180
	v_fma_f32 v111, v111, s10, v154
	v_fma_f32 v112, v112, s10, v181
	v_fma_f32 v113, v113, s10, v155
	v_mul_f32_e32 v130, v106, v106
	v_mul_f32_e32 v131, v107, v107
	v_fmac_f32_e32 v130, v108, v108
	v_fmac_f32_e32 v131, v109, v109
	v_fmac_f32_e32 v130, v110, v110
	v_fmac_f32_e32 v131, v111, v111
	v_fmac_f32_e32 v130, v112, v112
	v_fmac_f32_e32 v131, v113, v113
	v_cvt_pk_bf16_f32 v152, v106, v107
	v_cvt_pk_bf16_f32 v153, v108, v109
	v_cvt_pk_bf16_f32 v154, v110, v111
	v_cvt_pk_bf16_f32 v155, v112, v113
	v_lshlrev_b32_e32 v178, 16, v156
	v_lshlrev_b32_e32 v179, 16, v157
	v_lshlrev_b32_e32 v180, 16, v158
	v_lshlrev_b32_e32 v181, 16, v159
	v_and_b32_e32 v156, 0xffff0000, v156
	v_and_b32_e32 v157, 0xffff0000, v157
	v_and_b32_e32 v158, 0xffff0000, v158
	v_and_b32_e32 v159, 0xffff0000, v159
	v_fma_f32 v98, v98, s10, v178
	v_fma_f32 v99, v99, s10, v156
	v_fma_f32 v100, v100, s10, v179
	v_fma_f32 v101, v101, s10, v157
	v_fma_f32 v102, v102, s10, v180
	v_fma_f32 v103, v103, s10, v158
	v_fma_f32 v104, v104, s10, v181
	v_fma_f32 v105, v105, s10, v159
	v_fmac_f32_e32 v130, v98, v98
	v_fmac_f32_e32 v131, v99, v99
	v_fmac_f32_e32 v130, v100, v100
	v_fmac_f32_e32 v131, v101, v101
	v_fmac_f32_e32 v130, v102, v102
	v_fmac_f32_e32 v131, v103, v103
	v_fmac_f32_e32 v130, v104, v104
	v_fmac_f32_e32 v131, v105, v105
	v_cvt_pk_bf16_f32 v156, v98, v99
	v_cvt_pk_bf16_f32 v157, v100, v101
	v_cvt_pk_bf16_f32 v158, v102, v103
	v_cvt_pk_bf16_f32 v159, v104, v105
	v_add_f32_e32 v169, v130, v131
	s_nop 0
	v_permlane16_swap_b32_e32 v152, v154
	v_permlane16_swap_b32_e32 v153, v155
	v_permlane16_swap_b32_e32 v156, v158
	v_permlane16_swap_b32_e32 v157, v159
	global_store_dwordx4 v164, v[152:155], s[2:3]
	global_store_dwordx4 v164, v[156:159], s[2:3] offset:256
	v_add_u32_e32 v164, 0x8000, v164
	global_load_dwordx4 v[118:121], v0, s[2:3]
	global_load_dwordx4 v[106:109], v0, s[2:3] offset:256
	v_add_u32_e32 v0, 0x8000, v0
	s_waitcnt vmcnt(6)
; __device__ __forceinline__ u32x2 pk4(f32x4 v) { u32x2 r; r.x = cvt_pk_bf16(v[0], v[1]); r.y = cvt_pk_bf16(v[2], v[3]); return r; }
; template <int K>
; __device__ __forceinline__ void epilogue(const f32x4 (&acc)[2][2][4][2], const Unit& u, const EpiDesc& E, const Ctx& C, int wr, int wc, int fr, int fq) {
;     ...
; #pragma unroll
;         for (int ai = 0; ai < 2; ++ai)
; #pragma unroll
;         for (int mh = 0; mh < 2; ++mh) {
;             u32x2 h[2][2][2];
; #pragma unroll
;             for (int m2 = 0; m2 < 2; ++m2)
; #pragma unroll
;                 for (int bj = 0; bj < 2; ++bj)
; #pragma unroll
;                     for (int n = 0; n < 2; ++n) h[m2][bj][n] = *(const u32x2*)(C.XB + (size_t)(row0 + 128 * ai + 16 * (2 * mh + m2)) * DM + 256 * u.pn + 128 * bj + 16 * n + lc0);
; #pragma unroll
;             for (int m2 = 0; m2 < 2; ++m2) {
;                 const int m = 2 * mh + m2;
;                 const int row = row0 + 128 * ai + 16 * m;
;                 float* dst = C.PA + (size_t)row * DM;
;                 if (E.final_) {
;                     if (row < NPR) { const int b = row / TP, t = row - b * TP; if (t >= 16) dst = C.out + OFF_YP + ((size_t)b * 4096 + (t - 16)) * 1024; }
;                     else if (row < MR) dst = C.out + OFF_YS + (size_t)(row - NPR) * 1024;
;                 }
;                 float ss = 0.f;
; #pragma unroll
;                 for (int bj = 0; bj < 2; ++bj)
; #pragma unroll
;                     for (int n = 0; n < 2; ++n) {
;                         const int col = 256 * u.pn + 128 * bj + 16 * n + lc0;
;                         const f32x4 hv = unpk4(h[m2][bj][n]) + acc[ai][bj][m][n] * E.alpha;
;                         if (E.final_) *(f32x4*)(dst + col) = hv;
;                         else {
;                             *(u32x2*)(C.XB + (size_t)row * DM + col) = pk4(hv);
;                             ss += hv[0] * hv[0] + hv[1] * hv[1] + hv[2] * hv[2] + hv[3] * hv[3];
;                         }
;                     }
;                 if (!E.final_) {
;                     ss += __shfl_xor(ss, 16); ss += __shfl_xor(ss, 32);
;                     if (fq == 0) unsafeAtomicAdd(E.rss_out + row, ss);
;                 }
	v_permlane16_swap_b32_e32 v160, v162
	v_permlane16_swap_b32_e32 v161, v163
	v_permlane16_swap_b32_e32 v122, v124
	v_permlane16_swap_b32_e32 v123, v125
	v_lshlrev_b32_e32 v178, 16, v160
	v_lshlrev_b32_e32 v179, 16, v161
	v_lshlrev_b32_e32 v180, 16, v162
	v_lshlrev_b32_e32 v181, 16, v163
	v_and_b32_e32 v160, 0xffff0000, v160
	v_and_b32_e32 v161, 0xffff0000, v161
	v_and_b32_e32 v162, 0xffff0000, v162
	v_and_b32_e32 v163, 0xffff0000, v163
	v_fma_f32 v90, v90, s10, v178
	v_fma_f32 v91, v91, s10, v160
	v_fma_f32 v92, v92, s10, v179
	v_fma_f32 v93, v93, s10, v161
	v_fma_f32 v94, v94, s10, v180
	v_fma_f32 v95, v95, s10, v162
	v_fma_f32 v96, v96, s10, v181
	v_fma_f32 v97, v97, s10, v163
	v_mul_f32_e32 v130, v90, v90
	v_mul_f32_e32 v131, v91, v91
	v_fmac_f32_e32 v130, v92, v92
	v_fmac_f32_e32 v131, v93, v93
	v_fmac_f32_e32 v130, v94, v94
	v_fmac_f32_e32 v131, v95, v95
	v_fmac_f32_e32 v130, v96, v96
	v_fmac_f32_e32 v131, v97, v97
	v_cvt_pk_bf16_f32 v160, v90, v91
	v_cvt_pk_bf16_f32 v161, v92, v93
	v_cvt_pk_bf16_f32 v162, v94, v95
	v_cvt_pk_bf16_f32 v163, v96, v97
	v_lshlrev_b32_e32 v178, 16, v122
	v_lshlrev_b32_e32 v179, 16, v123
	v_lshlrev_b32_e32 v180, 16, v124
	v_lshlrev_b32_e32 v181, 16, v125
	v_and_b32_e32 v122, 0xffff0000, v122
	v_and_b32_e32 v123, 0xffff0000, v123
	v_and_b32_e32 v124, 0xffff0000, v124
	v_and_b32_e32 v125, 0xffff0000, v125
	v_fma_f32 v82, v82, s10, v178
	v_fma_f32 v83, v83, s10, v122
	v_fma_f32 v84, v84, s10, v179
	v_fma_f32 v85, v85, s10, v123
	v_fma_f32 v86, v86, s10, v180
	v_fma_f32 v87, v87, s10, v124
	v_fma_f32 v88, v88, s10, v181
	v_fma_f32 v89, v89, s10, v125
	v_fmac_f32_e32 v130, v82, v82
	v_fmac_f32_e32 v131, v83, v83
	v_fmac_f32_e32 v130, v84, v84
	v_fmac_f32_e32 v131, v85, v85
	v_fmac_f32_e32 v130, v86, v86
	v_fmac_f32_e32 v131, v87, v87
	v_fmac_f32_e32 v130, v88, v88
	v_fmac_f32_e32 v131, v89, v89
	v_cvt_pk_bf16_f32 v122, v82, v83
	v_cvt_pk_bf16_f32 v123, v84, v85
	v_cvt_pk_bf16_f32 v124, v86, v87
	v_cvt_pk_bf16_f32 v125, v88, v89
	v_add_f32_e32 v170, v130, v131
	s_nop 0
	v_permlane16_swap_b32_e32 v160, v162
	v_permlane16_swap_b32_e32 v161, v163
	v_permlane16_swap_b32_e32 v122, v124
	v_permlane16_swap_b32_e32 v123, v125
	global_store_dwordx4 v164, v[160:163], s[2:3]
	global_store_dwordx4 v164, v[122:125], s[2:3] offset:256
	v_add_u32_e32 v164, 0x8000, v164
	global_load_dwordx4 v[110:113], v0, s[2:3]
	global_load_dwordx4 v[98:101], v0, s[2:3] offset:256
	v_add_u32_e32 v0, 0x8000, v0
	s_waitcnt vmcnt(8)
	v_permlane16_swap_b32_e32 v126, v128
	v_permlane16_swap_b32_e32 v127, v129
	v_permlane16_swap_b32_e32 v114, v116
	v_permlane16_swap_b32_e32 v115, v117
	v_lshlrev_b32_e32 v178, 16, v126
	v_lshlrev_b32_e32 v179, 16, v127
	v_lshlrev_b32_e32 v180, 16, v128
	v_lshlrev_b32_e32 v181, 16, v129
	v_and_b32_e32 v126, 0xffff0000, v126
	v_and_b32_e32 v127, 0xffff0000, v127
	v_and_b32_e32 v128, 0xffff0000, v128
	v_and_b32_e32 v129, 0xffff0000, v129
	v_fma_f32 v74, v74, s10, v178
	v_fma_f32 v75, v75, s10, v126
	v_fma_f32 v76, v76, s10, v179
	v_fma_f32 v77, v77, s10, v127
	v_fma_f32 v78, v78, s10, v180
	v_fma_f32 v79, v79, s10, v128
	v_fma_f32 v80, v80, s10, v181
	v_fma_f32 v81, v81, s10, v129
	v_mul_f32_e32 v130, v74, v74
	v_mul_f32_e32 v131, v75, v75
	v_fmac_f32_e32 v130, v76, v76
	v_fmac_f32_e32 v131, v77, v77
	v_fmac_f32_e32 v130, v78, v78
	v_fmac_f32_e32 v131, v79, v79
	v_fmac_f32_e32 v130, v80, v80
	v_fmac_f32_e32 v131, v81, v81
	v_cvt_pk_bf16_f32 v126, v74, v75
	v_cvt_pk_bf16_f32 v127, v76, v77
	v_cvt_pk_bf16_f32 v128, v78, v79
	v_cvt_pk_bf16_f32 v129, v80, v81
	v_lshlrev_b32_e32 v178, 16, v114
	v_lshlrev_b32_e32 v179, 16, v115
	v_lshlrev_b32_e32 v180, 16, v116
	v_lshlrev_b32_e32 v181, 16, v117
	v_and_b32_e32 v114, 0xffff0000, v114
	v_and_b32_e32 v115, 0xffff0000, v115
	v_and_b32_e32 v116, 0xffff0000, v116
	v_and_b32_e32 v117, 0xffff0000, v117
	v_fma_f32 v66, v66, s10, v178
	v_fma_f32 v67, v67, s10, v114
	v_fma_f32 v68, v68, s10, v179
	v_fma_f32 v69, v69, s10, v115
	v_fma_f32 v70, v70, s10, v180
	v_fma_f32 v71, v71, s10, v116
	v_fma_f32 v72, v72, s10, v181
	v_fma_f32 v73, v73, s10, v117
	v_fmac_f32_e32 v130, v66, v66
	v_fmac_f32_e32 v131, v67, v67
	v_fmac_f32_e32 v130, v68, v68
	v_fmac_f32_e32 v131, v69, v69
	v_fmac_f32_e32 v130, v70, v70
	v_fmac_f32_e32 v131, v71, v71
	v_fmac_f32_e32 v130, v72, v72
	v_fmac_f32_e32 v131, v73, v73
	v_cvt_pk_bf16_f32 v114, v66, v67
	v_cvt_pk_bf16_f32 v115, v68, v69
	v_cvt_pk_bf16_f32 v116, v70, v71
	v_cvt_pk_bf16_f32 v117, v72, v73
	v_add_f32_e32 v171, v130, v131
	s_nop 0
	v_permlane16_swap_b32_e32 v126, v128
	v_permlane16_swap_b32_e32 v127, v129
	v_permlane16_swap_b32_e32 v114, v116
	v_permlane16_swap_b32_e32 v115, v117
	global_store_dwordx4 v164, v[126:129], s[2:3]
	global_store_dwordx4 v164, v[114:117], s[2:3] offset:256
	v_add_u32_e32 v164, 0x28000, v164
	global_load_dwordx4 v[102:105], v0, s[2:3]
	global_load_dwordx4 v[90:93], v0, s[2:3] offset:256
	v_add_u32_e32 v0, 0x8000, v0
	s_nop 1
	v_permlane16_swap_b32_e32 v168, v169
	v_permlane16_swap_b32_e32 v170, v171
	v_add_f32_e32 v168, v168, v169
	v_add_f32_e32 v170, v170, v171
	s_nop 1
	v_permlane32_swap_b32_e32 v168, v170
	v_add_f32_e32 v168, v168, v170
	global_atomic_add_f32 v132, v168, s[4:5]
	s_waitcnt vmcnt(9)
; __device__ __forceinline__ u32x2 pk4(f32x4 v) { u32x2 r; r.x = cvt_pk_bf16(v[0], v[1]); r.y = cvt_pk_bf16(v[2], v[3]); return r; }
; template <int K>
; __device__ __forceinline__ void epilogue(const f32x4 (&acc)[2][2][4][2], const Unit& u, const EpiDesc& E, const Ctx& C, int wr, int wc, int fr, int fq) {
;     ...
; #pragma unroll
;         for (int ai = 0; ai < 2; ++ai)
; #pragma unroll
;         for (int mh = 0; mh < 2; ++mh) {
;             u32x2 h[2][2][2];
; #pragma unroll
;             for (int m2 = 0; m2 < 2; ++m2)
; #pragma unroll
;                 for (int bj = 0; bj < 2; ++bj)
; #pragma unroll
;                     for (int n = 0; n < 2; ++n) h[m2][bj][n] = *(const u32x2*)(C.XB + (size_t)(row0 + 128 * ai + 16 * (2 * mh + m2)) * DM + 256 * u.pn + 128 * bj + 16 * n + lc0);
; #pragma unroll
;             for (int m2 = 0; m2 < 2; ++m2) {
;                 const int m = 2 * mh + m2;
;                 const int row = row0 + 128 * ai + 16 * m;
;                 float* dst = C.PA + (size_t)row * DM;
;                 if (E.final_) {
;                     if (row < NPR) { const int b = row / TP, t = row - b * TP; if (t >= 16) dst = C.out + OFF_YP + ((size_t)b * 4096 + (t - 16)) * 1024; }
;                     else if (row < MR) dst = C.out + OFF_YS + (size_t)(row - NPR) * 1024;
;                 }
;                 float ss = 0.f;
; #pragma unroll
;                 for (int bj = 0; bj < 2; ++bj)
; #pragma unroll
;                     for (int n = 0; n < 2; ++n) {
;                         const int col = 256 * u.pn + 128 * bj + 16 * n + lc0;
;                         const f32x4 hv = unpk4(h[m2][bj][n]) + acc[ai][bj][m][n] * E.alpha;
;                         if (E.final_) *(f32x4*)(dst + col) = hv;
;                         else {
;                             *(u32x2*)(C.XB + (size_t)row * DM + col) = pk4(hv);
;                             ss += hv[0] * hv[0] + hv[1] * hv[1] + hv[2] * hv[2] + hv[3] * hv[3];
;                         }
;                     }
;                 if (!E.final_) {
;                     ss += __shfl_xor(ss, 16); ss += __shfl_xor(ss, 32);
;                     if (fq == 0) unsafeAtomicAdd(E.rss_out + row, ss);
;                 }
	v_permlane16_swap_b32_e32 v118, v120
	v_permlane16_swap_b32_e32 v119, v121
	v_permlane16_swap_b32_e32 v106, v108
	v_permlane16_swap_b32_e32 v107, v109
	v_lshlrev_b32_e32 v178, 16, v118
	v_lshlrev_b32_e32 v179, 16, v119
	v_lshlrev_b32_e32 v180, 16, v120
	v_lshlrev_b32_e32 v181, 16, v121
	v_and_b32_e32 v118, 0xffff0000, v118
	v_and_b32_e32 v119, 0xffff0000, v119
	v_and_b32_e32 v120, 0xffff0000, v120
	v_and_b32_e32 v121, 0xffff0000, v121
	v_fma_f32 v58, v58, s10, v178
	v_fma_f32 v59, v59, s10, v118
	v_fma_f32 v60, v60, s10, v179
	v_fma_f32 v61, v61, s10, v119
	v_fma_f32 v62, v62, s10, v180
	v_fma_f32 v63, v63, s10, v120
	v_fma_f32 v64, v64, s10, v181
	v_fma_f32 v65, v65, s10, v121
	v_mul_f32_e32 v130, v58, v58
	v_mul_f32_e32 v131, v59, v59
	v_fmac_f32_e32 v130, v60, v60
	v_fmac_f32_e32 v131, v61, v61
	v_fmac_f32_e32 v130, v62, v62
	v_fmac_f32_e32 v131, v63, v63
	v_fmac_f32_e32 v130, v64, v64
	v_fmac_f32_e32 v131, v65, v65
	v_cvt_pk_bf16_f32 v118, v58, v59
	v_cvt_pk_bf16_f32 v119, v60, v61
	v_cvt_pk_bf16_f32 v120, v62, v63
	v_cvt_pk_bf16_f32 v121, v64, v65
	v_lshlrev_b32_e32 v178, 16, v106
	v_lshlrev_b32_e32 v179, 16, v107
	v_lshlrev_b32_e32 v180, 16, v108
	v_lshlrev_b32_e32 v181, 16, v109
	v_and_b32_e32 v106, 0xffff0000, v106
	v_and_b32_e32 v107, 0xffff0000, v107
	v_and_b32_e32 v108, 0xffff0000, v108
	v_and_b32_e32 v109, 0xffff0000, v109
	v_fma_f32 v50, v50, s10, v178
	v_fma_f32 v51, v51, s10, v106
	v_fma_f32 v52, v52, s10, v179
	v_fma_f32 v53, v53, s10, v107
	v_fma_f32 v54, v54, s10, v180
	v_fma_f32 v55, v55, s10, v108
	v_fma_f32 v56, v56, s10, v181
	v_fma_f32 v57, v57, s10, v109
	v_fmac_f32_e32 v130, v50, v50
	v_fmac_f32_e32 v131, v51, v51
	v_fmac_f32_e32 v130, v52, v52
	v_fmac_f32_e32 v131, v53, v53
	v_fmac_f32_e32 v130, v54, v54
	v_fmac_f32_e32 v131, v55, v55
	v_fmac_f32_e32 v130, v56, v56
	v_fmac_f32_e32 v131, v57, v57
	v_cvt_pk_bf16_f32 v106, v50, v51
	v_cvt_pk_bf16_f32 v107, v52, v53
	v_cvt_pk_bf16_f32 v108, v54, v55
	v_cvt_pk_bf16_f32 v109, v56, v57
	v_add_f32_e32 v168, v130, v131
	s_nop 0
	v_permlane16_swap_b32_e32 v118, v120
	v_permlane16_swap_b32_e32 v119, v121
	v_permlane16_swap_b32_e32 v106, v108
	v_permlane16_swap_b32_e32 v107, v109
	global_store_dwordx4 v164, v[118:121], s[2:3]
	global_store_dwordx4 v164, v[106:109], s[2:3] offset:256
	v_add_u32_e32 v164, 0x8000, v164
	global_load_dwordx4 v[94:97], v0, s[2:3]
	global_load_dwordx4 v[82:85], v0, s[2:3] offset:256
	s_waitcnt vmcnt(9)
	v_permlane16_swap_b32_e32 v110, v112
	v_permlane16_swap_b32_e32 v111, v113
	v_permlane16_swap_b32_e32 v98, v100
	v_permlane16_swap_b32_e32 v99, v101
	v_lshlrev_b32_e32 v178, 16, v110
	v_lshlrev_b32_e32 v179, 16, v111
	v_lshlrev_b32_e32 v180, 16, v112
	v_lshlrev_b32_e32 v181, 16, v113
	v_and_b32_e32 v110, 0xffff0000, v110
	v_and_b32_e32 v111, 0xffff0000, v111
	v_and_b32_e32 v112, 0xffff0000, v112
	v_and_b32_e32 v113, 0xffff0000, v113
	v_fma_f32 v42, v42, s10, v178
	v_fma_f32 v43, v43, s10, v110
	v_fma_f32 v44, v44, s10, v179
	v_fma_f32 v45, v45, s10, v111
	v_fma_f32 v46, v46, s10, v180
	v_fma_f32 v47, v47, s10, v112
	v_fma_f32 v48, v48, s10, v181
	v_fma_f32 v49, v49, s10, v113
	v_mul_f32_e32 v130, v42, v42
	v_mul_f32_e32 v131, v43, v43
	v_fmac_f32_e32 v130, v44, v44
	v_fmac_f32_e32 v131, v45, v45
	v_fmac_f32_e32 v130, v46, v46
	v_fmac_f32_e32 v131, v47, v47
	v_fmac_f32_e32 v130, v48, v48
	v_fmac_f32_e32 v131, v49, v49
	v_cvt_pk_bf16_f32 v110, v42, v43
	v_cvt_pk_bf16_f32 v111, v44, v45
	v_cvt_pk_bf16_f32 v112, v46, v47
	v_cvt_pk_bf16_f32 v113, v48, v49
	v_lshlrev_b32_e32 v178, 16, v98
	v_lshlrev_b32_e32 v179, 16, v99
	v_lshlrev_b32_e32 v180, 16, v100
	v_lshlrev_b32_e32 v181, 16, v101
	v_and_b32_e32 v98, 0xffff0000, v98
	v_and_b32_e32 v99, 0xffff0000, v99
	v_and_b32_e32 v100, 0xffff0000, v100
	v_and_b32_e32 v101, 0xffff0000, v101
	v_fma_f32 v34, v34, s10, v178
	v_fma_f32 v35, v35, s10, v98
	v_fma_f32 v36, v36, s10, v179
	v_fma_f32 v37, v37, s10, v99
	v_fma_f32 v38, v38, s10, v180
	v_fma_f32 v39, v39, s10, v100
	v_fma_f32 v40, v40, s10, v181
	v_fma_f32 v41, v41, s10, v101
	v_fmac_f32_e32 v130, v34, v34
	v_fmac_f32_e32 v131, v35, v35
	v_fmac_f32_e32 v130, v36, v36
	v_fmac_f32_e32 v131, v37, v37
	v_fmac_f32_e32 v130, v38, v38
	v_fmac_f32_e32 v131, v39, v39
	v_fmac_f32_e32 v130, v40, v40
	v_fmac_f32_e32 v131, v41, v41
	v_cvt_pk_bf16_f32 v98, v34, v35
	v_cvt_pk_bf16_f32 v99, v36, v37
	v_cvt_pk_bf16_f32 v100, v38, v39
	v_cvt_pk_bf16_f32 v101, v40, v41
	v_add_f32_e32 v169, v130, v131
	s_nop 0
	v_permlane16_swap_b32_e32 v110, v112
	v_permlane16_swap_b32_e32 v111, v113
	v_permlane16_swap_b32_e32 v98, v100
	v_permlane16_swap_b32_e32 v99, v101
	global_store_dwordx4 v164, v[110:113], s[2:3]
	global_store_dwordx4 v164, v[98:101], s[2:3] offset:256
	v_add_u32_e32 v164, 0x8000, v164
	s_waitcnt vmcnt(7)
; __device__ __forceinline__ u32x2 pk4(f32x4 v) { u32x2 r; r.x = cvt_pk_bf16(v[0], v[1]); r.y = cvt_pk_bf16(v[2], v[3]); return r; }
; template <int K>
; __device__ __forceinline__ void epilogue(const f32x4 (&acc)[2][2][4][2], const Unit& u, const EpiDesc& E, const Ctx& C, int wr, int wc, int fr, int fq) {
;     ...
; #pragma unroll
;         for (int ai = 0; ai < 2; ++ai)
; #pragma unroll
;         for (int mh = 0; mh < 2; ++mh) {
;             u32x2 h[2][2][2];
; #pragma unroll
;             for (int m2 = 0; m2 < 2; ++m2)
; #pragma unroll
;                 for (int bj = 0; bj < 2; ++bj)
; #pragma unroll
;                     for (int n = 0; n < 2; ++n) h[m2][bj][n] = *(const u32x2*)(C.XB + (size_t)(row0 + 128 * ai + 16 * (2 * mh + m2)) * DM + 256 * u.pn + 128 * bj + 16 * n + lc0);
; #pragma unroll
;             for (int m2 = 0; m2 < 2; ++m2) {
;                 const int m = 2 * mh + m2;
;                 const int row = row0 + 128 * ai + 16 * m;
;                 float* dst = C.PA + (size_t)row * DM;
;                 if (E.final_) {
;                     if (row < NPR) { const int b = row / TP, t = row - b * TP; if (t >= 16) dst = C.out + OFF_YP + ((size_t)b * 4096 + (t - 16)) * 1024; }
;                     else if (row < MR) dst = C.out + OFF_YS + (size_t)(row - NPR) * 1024;
;                 }
;                 float ss = 0.f;
; #pragma unroll
;                 for (int bj = 0; bj < 2; ++bj)
; #pragma unroll
;                     for (int n = 0; n < 2; ++n) {
;                         const int col = 256 * u.pn + 128 * bj + 16 * n + lc0;
;                         const f32x4 hv = unpk4(h[m2][bj][n]) + acc[ai][bj][m][n] * E.alpha;
;                         if (E.final_) *(f32x4*)(dst + col) = hv;
;                         else {
;                             *(u32x2*)(C.XB + (size_t)row * DM + col) = pk4(hv);
;                             ss += hv[0] * hv[0] + hv[1] * hv[1] + hv[2] * hv[2] + hv[3] * hv[3];
;                         }
;                     }
;                 if (!E.final_) {
;                     ss += __shfl_xor(ss, 16); ss += __shfl_xor(ss, 32);
;                     if (fq == 0) unsafeAtomicAdd(E.rss_out + row, ss);
;                 }
	v_permlane16_swap_b32_e32 v102, v104
	v_permlane16_swap_b32_e32 v103, v105
	v_permlane16_swap_b32_e32 v90, v92
	v_permlane16_swap_b32_e32 v91, v93
	v_lshlrev_b32_e32 v178, 16, v102
	v_lshlrev_b32_e32 v179, 16, v103
	v_lshlrev_b32_e32 v180, 16, v104
	v_lshlrev_b32_e32 v181, 16, v105
	v_and_b32_e32 v102, 0xffff0000, v102
	v_and_b32_e32 v103, 0xffff0000, v103
	v_and_b32_e32 v104, 0xffff0000, v104
	v_and_b32_e32 v105, 0xffff0000, v105
	v_fma_f32 v26, v26, s10, v178
	v_fma_f32 v27, v27, s10, v102
	v_fma_f32 v28, v28, s10, v179
	v_fma_f32 v29, v29, s10, v103
	v_fma_f32 v30, v30, s10, v180
	v_fma_f32 v31, v31, s10, v104
	v_fma_f32 v32, v32, s10, v181
	v_fma_f32 v33, v33, s10, v105
	v_mul_f32_e32 v130, v26, v26
	v_mul_f32_e32 v131, v27, v27
	v_fmac_f32_e32 v130, v28, v28
	v_fmac_f32_e32 v131, v29, v29
	v_fmac_f32_e32 v130, v30, v30
	v_fmac_f32_e32 v131, v31, v31
	v_fmac_f32_e32 v130, v32, v32
	v_fmac_f32_e32 v131, v33, v33
	v_cvt_pk_bf16_f32 v102, v26, v27
	v_cvt_pk_bf16_f32 v103, v28, v29
	v_cvt_pk_bf16_f32 v104, v30, v31
	v_cvt_pk_bf16_f32 v105, v32, v33
	v_lshlrev_b32_e32 v178, 16, v90
	v_lshlrev_b32_e32 v179, 16, v91
	v_lshlrev_b32_e32 v180, 16, v92
	v_lshlrev_b32_e32 v181, 16, v93
	v_and_b32_e32 v90, 0xffff0000, v90
	v_and_b32_e32 v91, 0xffff0000, v91
	v_and_b32_e32 v92, 0xffff0000, v92
	v_and_b32_e32 v93, 0xffff0000, v93
	v_fma_f32 v18, v18, s10, v178
	v_fma_f32 v19, v19, s10, v90
	v_fma_f32 v20, v20, s10, v179
	v_fma_f32 v21, v21, s10, v91
	v_fma_f32 v22, v22, s10, v180
	v_fma_f32 v23, v23, s10, v92
	v_fma_f32 v24, v24, s10, v181
	v_fma_f32 v25, v25, s10, v93
	v_fmac_f32_e32 v130, v18, v18
	v_fmac_f32_e32 v131, v19, v19
	v_fmac_f32_e32 v130, v20, v20
	v_fmac_f32_e32 v131, v21, v21
	v_fmac_f32_e32 v130, v22, v22
	v_fmac_f32_e32 v131, v23, v23
	v_fmac_f32_e32 v130, v24, v24
	v_fmac_f32_e32 v131, v25, v25
	v_cvt_pk_bf16_f32 v90, v18, v19
	v_cvt_pk_bf16_f32 v91, v20, v21
	v_cvt_pk_bf16_f32 v92, v22, v23
	v_cvt_pk_bf16_f32 v93, v24, v25
	v_add_f32_e32 v170, v130, v131
	s_nop 0
	v_permlane16_swap_b32_e32 v102, v104
	v_permlane16_swap_b32_e32 v103, v105
	v_permlane16_swap_b32_e32 v90, v92
	v_permlane16_swap_b32_e32 v91, v93
	global_store_dwordx4 v164, v[102:105], s[2:3]
	global_store_dwordx4 v164, v[90:93], s[2:3] offset:256
	v_add_u32_e32 v164, 0x8000, v164
	s_waitcnt vmcnt(4)
	v_permlane16_swap_b32_e32 v94, v96
	v_permlane16_swap_b32_e32 v95, v97
	v_permlane16_swap_b32_e32 v82, v84
	v_permlane16_swap_b32_e32 v83, v85
	v_lshlrev_b32_e32 v178, 16, v94
	v_lshlrev_b32_e32 v179, 16, v95
	v_lshlrev_b32_e32 v180, 16, v96
	v_lshlrev_b32_e32 v181, 16, v97
	v_and_b32_e32 v94, 0xffff0000, v94
	v_and_b32_e32 v95, 0xffff0000, v95
	v_and_b32_e32 v96, 0xffff0000, v96
	v_and_b32_e32 v97, 0xffff0000, v97
	v_fma_f32 v10, v10, s10, v178
	v_fma_f32 v11, v11, s10, v94
	v_fma_f32 v12, v12, s10, v179
	v_fma_f32 v13, v13, s10, v95
	v_fma_f32 v14, v14, s10, v180
	v_fma_f32 v15, v15, s10, v96
	v_fma_f32 v16, v16, s10, v181
	v_fma_f32 v17, v17, s10, v97
	v_mul_f32_e32 v130, v10, v10
	v_mul_f32_e32 v131, v11, v11
	v_fmac_f32_e32 v130, v12, v12
	v_fmac_f32_e32 v131, v13, v13
	v_fmac_f32_e32 v130, v14, v14
	v_fmac_f32_e32 v131, v15, v15
	v_fmac_f32_e32 v130, v16, v16
	v_fmac_f32_e32 v131, v17, v17
	v_cvt_pk_bf16_f32 v94, v10, v11
	v_cvt_pk_bf16_f32 v95, v12, v13
	v_cvt_pk_bf16_f32 v96, v14, v15
	v_cvt_pk_bf16_f32 v97, v16, v17
	v_lshlrev_b32_e32 v178, 16, v82
	v_lshlrev_b32_e32 v179, 16, v83
	v_lshlrev_b32_e32 v180, 16, v84
	v_lshlrev_b32_e32 v181, 16, v85
	v_and_b32_e32 v82, 0xffff0000, v82
	v_and_b32_e32 v83, 0xffff0000, v83
	v_and_b32_e32 v84, 0xffff0000, v84
	v_and_b32_e32 v85, 0xffff0000, v85
	v_fma_f32 v6, v6, s10, v178
	v_fma_f32 v7, v7, s10, v82
	v_fma_f32 v8, v8, s10, v179
	v_fma_f32 v9, v9, s10, v83
	v_fma_f32 v2, v2, s10, v180
	v_fma_f32 v3, v3, s10, v84
	v_fma_f32 v4, v4, s10, v181
	v_fma_f32 v5, v5, s10, v85
	v_fmac_f32_e32 v130, v6, v6
	v_fmac_f32_e32 v131, v7, v7
	v_fmac_f32_e32 v130, v8, v8
	v_fmac_f32_e32 v131, v9, v9
	v_fmac_f32_e32 v130, v2, v2
	v_fmac_f32_e32 v131, v3, v3
	v_fmac_f32_e32 v130, v4, v4
	v_fmac_f32_e32 v131, v5, v5
	v_cvt_pk_bf16_f32 v82, v6, v7
	v_cvt_pk_bf16_f32 v83, v8, v9
	v_cvt_pk_bf16_f32 v84, v2, v3
	v_cvt_pk_bf16_f32 v85, v4, v5
	v_add_f32_e32 v171, v130, v131
	s_nop 0
	v_permlane16_swap_b32_e32 v94, v96
	v_permlane16_swap_b32_e32 v95, v97
	v_permlane16_swap_b32_e32 v82, v84
	v_permlane16_swap_b32_e32 v83, v85
	global_store_dwordx4 v164, v[94:97], s[2:3]
	global_store_dwordx4 v164, v[82:85], s[2:3] offset:256
	s_nop 1
	v_permlane16_swap_b32_e32 v168, v169
	v_permlane16_swap_b32_e32 v170, v171
	v_add_f32_e32 v168, v168, v169
	v_add_f32_e32 v170, v170, v171
	s_nop 1
	v_permlane32_swap_b32_e32 v168, v170
	v_add_f32_e32 v168, v168, v170
	global_atomic_add_f32 v132, v168, s[4:5] offset:512
	s_branch .LBB0_245
